# combo2: light-phase edits (P7/P9 early query loads, sc1 on scattered fp8 stores, P8 batched cum chain, deferred queue atomic, parallel OFFS copy)
# speedup vs baseline: 1.0030x; 1.0030x over previous
; #define LAS __attribute__((address_space(3)))
; __device__ __forceinline__ void dma_kv_imgs(LAS unsigned char* Kimg, LAS unsigned char* Vimg, const f16_t* ksrc, const f16_t* vsrc, int wave, int lane, int pitch = NB) {
;     const int rl = lane >> 3, pos = lane & 7;
;     const int kc = pos ^ rl, vc = 2 * ((pos >> 1) ^ ((lane >> 4) & 3)) + (pos & 1);
;     const unsigned kd = (unsigned)__builtin_amdgcn_readfirstlane((int)(unsigned)(uintptr_t)Kimg), vd = (unsigned)__builtin_amdgcn_readfirstlane((int)(unsigned)(uintptr_t)Vimg);
; #pragma unroll
;     for (int i = 0; i < 4; ++i) { const int pc = wave + 8 * i, row = 8 * pc + rl;
;         glds16_asm(ksrc + (size_t)row * pitch + 8 * kc, (unsigned)__builtin_amdgcn_readfirstlane((int)(kd + pc * 1024)));
;         glds16_asm(vsrc + (size_t)row * pitch + 8 * vc, (unsigned)__builtin_amdgcn_readfirstlane((int)(vd + pc * 1024))); }
; }
; __device__ __forceinline__ void xattn_load_q(const f16_t* qp  , const float* gqm, int G, float maxgk, h16x8& q0, h16x8& q1, float& mb) {
;     const h16x8 r0v = *(const h16x8*)qp, r1v = *(const h16x8*)(qp + 32);
;     float q[16], ss = 0.f;
; #pragma unroll
;     for (int j = 0; j < 8; ++j) { q[j] = (float)r0v[j]; q[8 + j] = (float)r1v[j]; ss += q[j] * q[j] + q[8 + j] * q[8 + j]; }
;     ss += __shfl_xor(ss, 16); ss += __shfl_xor(ss, 32);
;     const float rn = 1.0f / sqrtf(ss * (1.0f / HD) + EPS);
;     float n2 = 0.f;
; #pragma unroll
;     for (int j = 0; j < 8; ++j) { q[j] *= rn * gqm[8 * G + j]; q[8 + j] *= rn * gqm[32 + 8 * G + j]; n2 += q[j] * q[j] + q[8 + j] * q[8 + j]; }
;     n2 += __shfl_xor(n2, 16); n2 += __shfl_xor(n2, 32);
.LBB0_921:
	s_lshl_b32 s0, s8, 1
	s_or_b32 s0, s0, s41
	s_ashr_i32 s1, s0, 31
	s_lshl_b64 s[2:3], s[0:1], 15
	v_lshl_add_u64 v[2:3], v[34:35], 0, s[2:3]
	v_lshl_add_u64 v[4:5], v[36:37], 0, s[2:3]
	v_lshl_add_u64 v[6:7], v[2:3], 0, v[44:45]
	s_mov_b32 s1, m0
	s_mov_b32 m0, s20
	s_nop 0
	global_load_lds_dwordx4 v[6:7], off
	s_mov_b32 m0, s1
	v_lshl_add_u64 v[6:7], v[4:5], 0, v[44:45]
	s_mov_b32 s1, m0
	s_mov_b32 m0, s21
	s_nop 0
	global_load_lds_dwordx4 v[6:7], off
	s_mov_b32 m0, s1
	v_lshl_add_u64 v[6:7], v[2:3], 0, v[46:47]
	s_mov_b32 s1, m0
	s_mov_b32 m0, s24
	s_nop 0
	global_load_lds_dwordx4 v[6:7], off
	s_mov_b32 m0, s1
	v_lshl_add_u64 v[6:7], v[4:5], 0, v[46:47]
	s_mov_b32 s1, m0
	s_mov_b32 m0, s25
	s_nop 0
	global_load_lds_dwordx4 v[6:7], off
	s_mov_b32 m0, s1
	v_lshl_add_u64 v[6:7], v[2:3], 0, v[48:49]
	s_mov_b32 s1, m0
	s_mov_b32 m0, s26
	s_nop 0
	global_load_lds_dwordx4 v[6:7], off
	s_mov_b32 m0, s1
	v_lshl_add_u64 v[6:7], v[4:5], 0, v[48:49]
	s_mov_b32 s1, m0
	s_mov_b32 m0, s27
	s_nop 0
	global_load_lds_dwordx4 v[6:7], off
	s_mov_b32 m0, s1
	v_lshl_add_u64 v[2:3], v[2:3], 0, v[50:51]
	s_mov_b32 s1, m0
	s_mov_b32 m0, s28
	s_nop 0
	global_load_lds_dwordx4 v[2:3], off
	s_mov_b32 m0, s1
	v_lshl_add_u64 v[2:3], v[4:5], 0, v[50:51]
	s_mov_b32 s1, m0
	s_mov_b32 m0, s29
	s_nop 0
	global_load_lds_dwordx4 v[2:3], off
	s_mov_b32 m0, s1
	s_or_b32 s0, s0, 1
	s_ashr_i32 s1, s0, 31
	s_lshl_b64 s[0:1], s[0:1], 15
	v_lshl_add_u64 v[2:3], v[34:35], 0, s[0:1]
	v_lshl_add_u64 v[4:5], v[36:37], 0, s[0:1]
	v_lshl_add_u64 v[6:7], v[2:3], 0, v[44:45]
	s_mov_b32 s0, m0
	s_mov_b32 m0, s30
	s_nop 0
	global_load_lds_dwordx4 v[6:7], off
	s_mov_b32 m0, s0
	v_lshl_add_u64 v[6:7], v[4:5], 0, v[44:45]
	s_mov_b32 s0, m0
	s_mov_b32 m0, s31
	s_nop 0
	global_load_lds_dwordx4 v[6:7], off
	s_mov_b32 m0, s0
	v_lshl_add_u64 v[6:7], v[2:3], 0, v[46:47]
	s_mov_b32 s0, m0
	s_mov_b32 m0, s34
	s_nop 0
	global_load_lds_dwordx4 v[6:7], off
	s_mov_b32 m0, s0
	v_lshl_add_u64 v[6:7], v[4:5], 0, v[46:47]
	s_mov_b32 s0, m0
	s_mov_b32 m0, s35
	s_nop 0
	global_load_lds_dwordx4 v[6:7], off
	s_mov_b32 m0, s0
	v_lshl_add_u64 v[6:7], v[2:3], 0, v[48:49]
	s_mov_b32 s0, m0
	s_mov_b32 m0, s36
	s_nop 0
	global_load_lds_dwordx4 v[6:7], off
	s_mov_b32 m0, s0
	s_lshl_b32 s42, s8, 7
	v_lshl_add_u64 v[6:7], v[4:5], 0, v[48:49]
	s_mov_b32 s0, m0
	s_mov_b32 m0, s37
	s_nop 0
	global_load_lds_dwordx4 v[6:7], off
	s_mov_b32 m0, s0
	s_add_i32 s42, s42, s17
	v_lshl_add_u64 v[2:3], v[2:3], 0, v[50:51]
	s_mov_b32 s0, m0
	s_mov_b32 m0, s38
	s_nop 0
	global_load_lds_dwordx4 v[2:3], off
	s_mov_b32 m0, s0
	s_lshl_b32 s8, s42, 1
	v_lshl_add_u64 v[2:3], v[4:5], 0, v[50:51]
	s_mov_b32 s0, m0
	s_mov_b32 m0, s39
	s_nop 0
	global_load_lds_dwordx4 v[2:3], off
	s_mov_b32 m0, s0
	v_lshl_add_u64 v[10:11], v[54:55], 0, s[8:9]
	global_load_dwordx4 v[2:5], v[10:11], off offset:64
	v_lshl_add_u64 v[12:13], v[58:59], 0, s[8:9]
	global_load_dwordx4 v[6:9], v[12:13], off offset:64
	global_load_dwordx4 v[82:85], v[10:11], off
	global_load_dwordx4 v[86:89], v[12:13], off
	s_nop 0
	global_load_dwordx4 v[10:13], v[38:39], off offset:400
	global_load_dwordx4 v[14:17], v[38:39], off offset:384
	global_load_dwordx4 v[18:21], v[38:39], off offset:272
	global_load_dwordx4 v[22:25], v[38:39], off offset:256
	s_waitcnt vmcnt(0)
	s_barrier
	s_waitcnt vmcnt(6)
	v_cvt_f32_f16_e32 v26, v9
	v_cvt_f32_f16_sdwa v27, v9 dst_sel:DWORD dst_unused:UNUSED_PAD src0_sel:WORD_1
	v_cvt_f32_f16_e32 v28, v8
	v_cvt_f32_f16_sdwa v29, v8 dst_sel:DWORD dst_unused:UNUSED_PAD src0_sel:WORD_1
	v_cvt_f32_f16_e32 v8, v2
	v_cvt_f32_f16_sdwa v9, v2 dst_sel:DWORD dst_unused:UNUSED_PAD src0_sel:WORD_1
	v_cvt_f32_f16_e32 v90, v5
	v_cvt_f32_f16_sdwa v91, v5 dst_sel:DWORD dst_unused:UNUSED_PAD src0_sel:WORD_1
	v_cvt_f32_f16_e32 v92, v4
	v_cvt_f32_f16_sdwa v93, v4 dst_sel:DWORD dst_unused:UNUSED_PAD src0_sel:WORD_1
	v_cvt_f32_f16_e32 v4, v3
	v_cvt_f32_f16_sdwa v5, v3 dst_sel:DWORD dst_unused:UNUSED_PAD src0_sel:WORD_1
	s_waitcnt vmcnt(5)
	v_cvt_f32_f16_e32 v96, v82
	v_cvt_f32_f16_sdwa v97, v82 dst_sel:DWORD dst_unused:UNUSED_PAD src0_sel:WORD_1
	v_cvt_f32_f16_e32 v60, v7
	v_cvt_f32_f16_sdwa v61, v7 dst_sel:DWORD dst_unused:UNUSED_PAD src0_sel:WORD_1
	v_cvt_f32_f16_e32 v64, v6
	v_cvt_f32_f16_sdwa v65, v6 dst_sel:DWORD dst_unused:UNUSED_PAD src0_sel:WORD_1
	v_cvt_f32_f16_e32 v6, v85
	v_cvt_f32_f16_sdwa v7, v85 dst_sel:DWORD dst_unused:UNUSED_PAD src0_sel:WORD_1
	v_cvt_f32_f16_e32 v94, v84
	v_cvt_f32_f16_sdwa v95, v84 dst_sel:DWORD dst_unused:UNUSED_PAD src0_sel:WORD_1
	v_cvt_f32_f16_e32 v84, v83
	v_cvt_f32_f16_sdwa v85, v83 dst_sel:DWORD dst_unused:UNUSED_PAD src0_sel:WORD_1
	v_pk_mul_f32 v[2:3], v[8:9], v[8:9]
	v_pk_mul_f32 v[100:101], v[4:5], v[4:5]
	v_pk_fma_f32 v[2:3], v[96:97], v[96:97], v[2:3]
	v_pk_fma_f32 v[100:101], v[84:85], v[84:85], v[100:101]
	v_add_f32_e32 v2, v2, v3
	v_pk_mul_f32 v[98:99], v[92:93], v[92:93]
	v_add_f32_e32 v2, v100, v2
	v_pk_fma_f32 v[98:99], v[94:95], v[94:95], v[98:99]
	v_add_f32_e32 v2, v101, v2
	v_pk_mul_f32 v[82:83], v[90:91], v[90:91]
	v_add_f32_e32 v2, v98, v2
	v_pk_fma_f32 v[82:83], v[6:7], v[6:7], v[82:83]
	v_add_f32_e32 v2, v99, v2
	v_add_f32_e32 v2, v82, v2
	v_add_f32_e32 v2, v83, v2
	ds_bpermute_b32 v3, v69, v2
	s_waitcnt vmcnt(4)
	v_cvt_f32_f16_e32 v62, v89
	v_cvt_f32_f16_sdwa v63, v89 dst_sel:DWORD dst_unused:UNUSED_PAD src0_sel:WORD_1
	v_cvt_f32_f16_e32 v82, v88
	v_cvt_f32_f16_sdwa v83, v88 dst_sel:DWORD dst_unused:UNUSED_PAD src0_sel:WORD_1
	s_waitcnt lgkmcnt(0)
	v_add_f32_e32 v102, v2, v3
	ds_bpermute_b32 v103, v70, v102
	v_cvt_f32_f16_e32 v88, v87
	v_cvt_f32_f16_sdwa v89, v87 dst_sel:DWORD dst_unused:UNUSED_PAD src0_sel:WORD_1
	v_pk_mul_f32 v[2:3], v[26:27], v[26:27]
	v_pk_mul_f32 v[98:99], v[64:65], v[64:65]
	s_waitcnt lgkmcnt(0)
; __device__ __forceinline__ unsigned pkh(float lo, float hi) { f32x2 v = {lo, hi}; h16x2 h = __builtin_convertvector(v, h16x2); return __builtin_bit_cast(unsigned, h); }
; __device__ __forceinline__ void xattn_load_q(const f16_t* qp  , const float* gqm, int G, float maxgk, h16x8& q0, h16x8& q1, float& mb) {
;     const h16x8 r0v = *(const h16x8*)qp, r1v = *(const h16x8*)(qp + 32);
;     float q[16], ss = 0.f;
; #pragma unroll
;     for (int j = 0; j < 8; ++j) { q[j] = (float)r0v[j]; q[8 + j] = (float)r1v[j]; ss += q[j] * q[j] + q[8 + j] * q[8 + j]; }
;     ss += __shfl_xor(ss, 16); ss += __shfl_xor(ss, 32);
;     const float rn = 1.0f / sqrtf(ss * (1.0f / HD) + EPS);
;     float n2 = 0.f;
; #pragma unroll
;     for (int j = 0; j < 8; ++j) { q[j] *= rn * gqm[8 * G + j]; q[8 + j] *= rn * gqm[32 + 8 * G + j]; n2 += q[j] * q[j] + q[8 + j] * q[8 + j]; }
;     n2 += __shfl_xor(n2, 16); n2 += __shfl_xor(n2, 32);
;     mb = (sqrtf(n2) * maxgk - BOUND_SHIFT) * LOG2E;
;     const float c = 0.125f * LOG2E;
;     u32x4 w0, w1;
;     w0.x = pkh(q[0] * c, q[1] * c); w0.y = pkh(q[2] * c, q[3] * c); w0.z = pkh(q[4] * c, q[5] * c); w0.w = pkh(q[6] * c, q[7] * c);
;     w1.x = pkh(q[8] * c, q[9] * c); w1.y = pkh(q[10] * c, q[11] * c); w1.z = pkh(q[12] * c, q[13] * c); w1.w = pkh(q[14] * c, q[15] * c);
;     q0 = __builtin_bit_cast(h16x8, w0); q1 = __builtin_bit_cast(h16x8, w1);
; }
	v_add_f32_e32 v87, v102, v103
	v_fmamk_f32 v87, v87, 0x3c800000, v74
	v_mul_f32_e32 v102, 0x4f800000, v87
	v_cmp_gt_f32_e32 vcc, s19, v87
	v_pk_fma_f32 v[104:105], v[62:63], v[62:63], v[2:3]
	v_pk_mul_f32 v[100:101], v[28:29], v[28:29]
	v_cndmask_b32_e32 v87, v87, v102, vcc
	v_sqrt_f32_e32 v106, v87
	v_pk_mul_f32 v[102:103], v[60:61], v[60:61]
	v_pk_fma_f32 v[100:101], v[82:83], v[82:83], v[100:101]
	v_pk_fma_f32 v[102:103], v[88:89], v[88:89], v[102:103]
	v_add_u32_e32 v2, -1, v106
	v_add_u32_e32 v3, 1, v106
	v_fma_f32 v107, -v2, v106, v87
	v_fma_f32 v108, -v3, v106, v87
	v_cmp_ge_f32_e64 s[0:1], 0, v107
	s_nop 1
	v_cndmask_b32_e64 v2, v106, v2, s[0:1]
	v_cmp_lt_f32_e64 s[0:1], 0, v108
	s_nop 1
	v_cndmask_b32_e64 v2, v2, v3, s[0:1]
	v_mul_f32_e32 v3, 0x37800000, v2
	v_cndmask_b32_e32 v2, v2, v3, vcc
	v_cmp_class_f32_e32 vcc, v87, v75
	s_nop 1
	v_cndmask_b32_e32 v2, v2, v87, vcc
	v_div_scale_f32 v3, s[0:1], v2, v2, 1.0
	v_rcp_f32_e32 v87, v3
	v_div_scale_f32 v106, vcc, 1.0, v2, 1.0
	v_fma_f32 v107, -v3, v87, 1.0
	v_fmac_f32_e32 v87, v107, v87
	v_mul_f32_e32 v107, v106, v87
	v_fma_f32 v108, -v3, v107, v106
	v_fmac_f32_e32 v107, v108, v87
	v_fma_f32 v3, -v3, v107, v106
	v_div_fmas_f32 v3, v3, v87, v107
	v_div_fixup_f32 v106, v3, v2, 1.0
	s_waitcnt vmcnt(3)
	v_pk_mul_f32 v[108:109], v[10:11], v[106:107] op_sel_hi:[1,0]
	s_waitcnt vmcnt(2)
	v_pk_mul_f32 v[110:111], v[16:17], v[106:107] op_sel_hi:[1,0]
	v_pk_mul_f32 v[112:113], v[14:15], v[106:107] op_sel_hi:[1,0]
	v_pk_mul_f32 v[92:93], v[108:109], v[92:93]
	v_pk_mul_f32 v[108:109], v[110:111], v[4:5]
	v_pk_mul_f32 v[110:111], v[112:113], v[8:9]
	v_pk_mul_f32 v[8:9], v[92:93], s[12:13] op_sel_hi:[1,0]
	v_pk_mul_f32 v[2:3], v[12:13], v[106:107] op_sel_hi:[1,0]
	v_cvt_pk_f16_f32 v4, v8, v9
	s_waitcnt vmcnt(1)
	v_pk_mul_f32 v[8:9], v[20:21], v[106:107] op_sel_hi:[1,0]
	v_pk_mul_f32 v[90:91], v[2:3], v[90:91]
	v_pk_mul_f32 v[6:7], v[8:9], v[6:7]
	v_pk_mul_f32 v[2:3], v[90:91], s[12:13] op_sel_hi:[1,0]
	v_pk_mul_f32 v[8:9], v[6:7], s[12:13] op_sel_hi:[1,0]
	v_pk_mul_f32 v[6:7], v[6:7], v[6:7]
	v_pk_mul_f32 v[112:113], v[108:109], s[12:13] op_sel_hi:[1,0]
	v_pk_fma_f32 v[6:7], v[90:91], v[90:91], v[6:7]
	v_pk_mul_f32 v[90:91], v[18:19], v[106:107] op_sel_hi:[1,0]
	v_cvt_pk_f16_f32 v9, v8, v9
	v_pk_mul_f32 v[90:91], v[90:91], v[94:95]
	v_pk_mul_f32 v[114:115], v[110:111], s[12:13] op_sel_hi:[1,0]
	v_pk_mul_f32 v[94:95], v[90:91], v[90:91]
	v_cvt_pk_f16_f32 v5, v2, v3
	v_pk_fma_f32 v[92:93], v[92:93], v[92:93], v[94:95]
	s_waitcnt vmcnt(0)
	v_pk_mul_f32 v[94:95], v[24:25], v[106:107] op_sel_hi:[1,0]
	v_pk_mul_f32 v[106:107], v[22:23], v[106:107] op_sel_hi:[1,0]
	v_pk_mul_f32 v[84:85], v[94:95], v[84:85]
	v_cvt_pk_f16_f32 v3, v112, v113
	v_pk_mul_f32 v[94:95], v[84:85], v[84:85]
	v_cvt_pk_f16_f32 v2, v114, v115
	v_pk_fma_f32 v[94:95], v[108:109], v[108:109], v[94:95]
	v_cvt_f32_f16_e32 v108, v86
	v_cvt_f32_f16_sdwa v109, v86 dst_sel:DWORD dst_unused:UNUSED_PAD src0_sel:WORD_1
	v_pk_mul_f32 v[86:87], v[106:107], v[96:97]
	v_pk_fma_f32 v[98:99], v[108:109], v[108:109], v[98:99]
	v_pk_mul_f32 v[96:97], v[86:87], v[86:87]
	s_nop 0
	v_pk_fma_f32 v[96:97], v[110:111], v[110:111], v[96:97]
	s_nop 0
	v_add_f32_e32 v8, v96, v97
	v_add_f32_e32 v8, v94, v8
	v_add_f32_e32 v8, v95, v8
	v_add_f32_e32 v8, v92, v8
	v_add_f32_e32 v8, v93, v8
	v_add_f32_e32 v6, v6, v8
	v_add_f32_e32 v92, v7, v6
	v_add_f32_e32 v6, v98, v99
	v_add_f32_e32 v6, v102, v6
	v_add_f32_e32 v6, v103, v6
	v_add_f32_e32 v6, v100, v6
	v_add_f32_e32 v6, v101, v6
	v_add_f32_e32 v6, v104, v6
	v_add_f32_e32 v94, v105, v6
	ds_bpermute_b32 v93, v69, v92
	ds_bpermute_b32 v95, v69, v94
	v_pk_mul_f32 v[6:7], v[90:91], s[12:13] op_sel_hi:[1,0]
	s_waitcnt lgkmcnt(1)
	v_add_f32_e32 v90, v92, v93
	s_waitcnt lgkmcnt(0)
	v_add_f32_e32 v92, v94, v95
	ds_bpermute_b32 v93, v70, v92
	ds_bpermute_b32 v91, v70, v90
	v_cvt_pk_f16_f32 v8, v6, v7
	v_pk_mul_f32 v[6:7], v[84:85], s[12:13] op_sel_hi:[1,0]
	s_waitcnt lgkmcnt(1)
	v_add_f32_e32 v85, v92, v93
	v_fmamk_f32 v85, v85, 0x3c800000, v74
	v_cvt_pk_f16_f32 v7, v6, v7
	s_waitcnt lgkmcnt(0)
	v_add_f32_e32 v6, v90, v91
	v_mul_f32_e32 v90, 0x4f800000, v85
	v_cmp_gt_f32_e32 vcc, s19, v85
	v_mul_f32_e32 v84, 0x4f800000, v6
	v_cmp_gt_f32_e64 s[0:1], s19, v6
	v_cndmask_b32_e32 v85, v85, v90, vcc
	v_sqrt_f32_e32 v90, v85
	v_cndmask_b32_e64 v91, v6, v84, s[0:1]
	v_sqrt_f32_e32 v92, v91
	v_add_u32_e32 v6, -1, v90
	v_fma_f32 v84, -v6, v90, v85
	v_cmp_ge_f32_e64 s[2:3], 0, v84
	v_add_u32_e32 v84, 1, v90
	s_nop 0
	v_cndmask_b32_e64 v6, v90, v6, s[2:3]
	v_fma_f32 v90, -v84, v90, v85
	v_cmp_lt_f32_e64 s[2:3], 0, v90
	s_nop 1
	v_cndmask_b32_e64 v6, v6, v84, s[2:3]
	v_mul_f32_e32 v84, 0x37800000, v6
	v_cndmask_b32_e32 v6, v6, v84, vcc
	v_cmp_class_f32_e32 vcc, v85, v75
	s_nop 1
	v_cndmask_b32_e32 v90, v6, v85, vcc
	v_div_scale_f32 v93, s[2:3], v90, v90, 1.0
	v_rcp_f32_e32 v94, v93
	v_pk_mul_f32 v[84:85], v[86:87], s[12:13] op_sel_hi:[1,0]
	s_nop 0
	v_cvt_pk_f16_f32 v6, v84, v85
	v_fma_f32 v84, -v93, v94, 1.0
	v_fmac_f32_e32 v94, v84, v94
	v_div_scale_f32 v84, vcc, 1.0, v90, 1.0
	v_mul_f32_e32 v86, v84, v94
	v_fma_f32 v87, -v93, v86, v84
	v_fmac_f32_e32 v86, v87, v94
	v_fma_f32 v84, -v93, v86, v84
	v_div_fmas_f32 v84, v84, v94, v86
	v_add_u32_e32 v85, -1, v92
	v_div_fixup_f32 v84, v84, v90, 1.0
	v_pk_mul_f32 v[22:23], v[22:23], v[84:85] op_sel_hi:[1,0]
	v_pk_mul_f32 v[14:15], v[14:15], v[84:85] op_sel_hi:[1,0]
	v_pk_mul_f32 v[22:23], v[22:23], v[108:109]
	v_pk_mul_f32 v[24:25], v[24:25], v[84:85] op_sel_hi:[1,0]
	v_pk_mul_f32 v[86:87], v[22:23], v[22:23]
	v_pk_mul_f32 v[64:65], v[14:15], v[64:65]
	v_pk_mul_f32 v[24:25], v[24:25], v[88:89]
	v_pk_mul_f32 v[16:17], v[16:17], v[84:85] op_sel_hi:[1,0]
	v_pk_fma_f32 v[14:15], v[64:65], v[64:65], v[86:87]
	v_pk_mul_f32 v[60:61], v[16:17], v[60:61]
	v_pk_mul_f32 v[16:17], v[24:25], v[24:25]
	v_pk_mul_f32 v[18:19], v[18:19], v[84:85] op_sel_hi:[1,0]
	v_pk_fma_f32 v[16:17], v[60:61], v[60:61], v[16:17]
	v_pk_mul_f32 v[18:19], v[18:19], v[82:83]
	v_pk_mul_f32 v[10:11], v[10:11], v[84:85] op_sel_hi:[1,0]
	v_add_f32_e32 v14, v14, v15
	v_pk_mul_f32 v[10:11], v[10:11], v[28:29]
	v_pk_mul_f32 v[28:29], v[18:19], v[18:19]
	v_pk_mul_f32 v[20:21], v[20:21], v[84:85] op_sel_hi:[1,0]
	v_add_f32_e32 v14, v16, v14
	v_pk_fma_f32 v[28:29], v[10:11], v[10:11], v[28:29]
	v_pk_mul_f32 v[20:21], v[20:21], v[62:63]
	v_pk_mul_f32 v[12:13], v[12:13], v[84:85] op_sel_hi:[1,0]
	v_add_f32_e32 v14, v17, v14
	v_pk_mul_f32 v[12:13], v[12:13], v[26:27]
	v_pk_mul_f32 v[26:27], v[20:21], v[20:21]
	v_add_f32_e32 v14, v28, v14
	v_pk_fma_f32 v[26:27], v[12:13], v[12:13], v[26:27]
	v_add_f32_e32 v14, v29, v14
	v_add_f32_e32 v14, v26, v14
	v_add_f32_e32 v14, v27, v14
	ds_bpermute_b32 v15, v69, v14
	v_fma_f32 v16, -v85, v92, v91
	v_add_u32_e32 v17, 1, v92
	v_cmp_ge_f32_e32 vcc, 0, v16
	v_fma_f32 v26, -v17, v92, v91
	s_waitcnt lgkmcnt(0)
; #define LAS __attribute__((address_space(3)))
; template <bool CAUSAL, bool SHARED> ...
;     const int fr = lane & 15, G = lane >> 4, qq = fr >> 2, p = fr & 3;
;     const int kof0 = fr * 128 + (((0 + G) ^ (fr & 7)) << 4), kof1 = fr * 128 + (((4 + G) ^ (fr & 7)) << 4);
;     const int vrow = (4 * G + qq) * 128 + p * 8, sw = (2 * G + (qq >> 1)) & 3;
;     const h16x8 ones = {(_Float16)1.0f, (_Float16)1.0f, (_Float16)1.0f, (_Float16)1.0f, (_Float16)1.0f, (_Float16)1.0f, (_Float16)1.0f, (_Float16)1.0f};
;     const f32x4 nma = {-mba, -mba, -mba, -mba}, nmb = {-mbb, -mbb, -mbb, -mbb};
;     f32x4 la = {0.f, 0.f, 0.f, 0.f}, lb = la;
;     h16x8 ka[4], kb[4];
;     ka[0] = *(LAS const h16x8*)(Ka + kof0); ka[1] = *(LAS const h16x8*)(Ka + kof1); ka[2] = *(LAS const h16x8*)(Ka + 2048 + kof0); ka[3] = *(LAS const h16x8*)(Ka + 2048 + kof1);
;     if (!SHARED) { kb[0] = *(LAS const h16x8*)(Kb + kof0); kb[1] = *(LAS const h16x8*)(Kb + kof1); kb[2] = *(LAS const h16x8*)(Kb + 2048 + kof0); kb[3] = *(LAS const h16x8*)(Kb + 2048 + kof1); }
;     for (int ks = 0; ks < nsteps; ++ks) {
;         LAS const unsigned char* va = Va + ks * 4096 + vrow; LAS const unsigned char* vb = Vb + ks * 4096 + vrow;
;         h16x4 fal[4], fah[4], fbl[4], fbh[4];
; #pragma unroll
;         for (int dt = 0; dt < 4; ++dt) { fal[dt] = vtr(va + ((dt ^ sw) << 5)); fah[dt] = vtr(va + 2048 + ((dt ^ sw) << 5));
;             if (!SHARED) { fbl[dt] = vtr(vb + ((dt ^ sw) << 5)); fbh[dt] = vtr(vb + 2048 + ((dt ^ sw) << 5)); } }
;         __builtin_amdgcn_sched_barrier(0);
;         f32x4 sa0, sa1, sb0, sb1;
;         sa0 = __builtin_amdgcn_mfma_f32_16x16x32_f16(ka[0], qa0, nma, 0, 0, 0); sb0 = __builtin_amdgcn_mfma_f32_16x16x32_f16(SHARED ? ka[0] : kb[0], qb0, nmb, 0, 0, 0);
; __device__ __forceinline__ void xattn_load_q(const f16_t* qp  , const float* gqm, int G, float maxgk, h16x8& q0, h16x8& q1, float& mb) {
;     ...
;     mb = (sqrtf(n2) * maxgk - BOUND_SHIFT) * LOG2E;
;     const float c = 0.125f * LOG2E;
;     u32x4 w0, w1;
;     w0.x = pkh(q[0] * c, q[1] * c); w0.y = pkh(q[2] * c, q[3] * c); w0.z = pkh(q[4] * c, q[5] * c); w0.w = pkh(q[6] * c, q[7] * c);
;     w1.x = pkh(q[8] * c, q[9] * c); w1.y = pkh(q[10] * c, q[11] * c); w1.z = pkh(q[12] * c, q[13] * c); w1.w = pkh(q[14] * c, q[15] * c);
;     q0 = __builtin_bit_cast(h16x8, w0); q1 = __builtin_bit_cast(h16x8, w1);
	v_add_f32_e32 v14, v14, v15
	ds_bpermute_b32 v15, v70, v14
	v_cndmask_b32_e32 v16, v92, v85, vcc
	v_cmp_lt_f32_e32 vcc, 0, v26
	v_pk_mul_f32 v[10:11], v[10:11], s[12:13] op_sel_hi:[1,0]
	s_waitcnt lgkmcnt(0)
	v_add_f32_e32 v14, v14, v15
	v_cndmask_b32_e32 v16, v16, v17, vcc
	v_mul_f32_e32 v15, 0x4f800000, v14
	v_cmp_gt_f32_e32 vcc, s19, v14
	v_mul_f32_e32 v17, 0x37800000, v16
	v_cndmask_b32_e64 v16, v16, v17, s[0:1]
	v_cndmask_b32_e32 v14, v14, v15, vcc
	v_sqrt_f32_e32 v15, v14
	v_cmp_class_f32_e64 s[0:1], v91, v75
	s_nop 1
	v_cndmask_b32_e64 v26, v16, v91, s[0:1]
	v_add_u32_e32 v16, -1, v15
	v_fma_f32 v17, -v16, v15, v14
	v_cmp_ge_f32_e64 s[0:1], 0, v17
	v_add_u32_e32 v17, 1, v15
	s_nop 0
	v_cndmask_b32_e64 v16, v15, v16, s[0:1]
	v_fma_f32 v15, -v17, v15, v14
	v_cmp_lt_f32_e64 s[0:1], 0, v15
	s_nop 1
	v_cndmask_b32_e64 v15, v16, v17, s[0:1]
	v_mul_f32_e32 v16, 0x37800000, v15
	v_cndmask_b32_e32 v15, v15, v16, vcc
	v_cmp_class_f32_e32 vcc, v14, v75
	v_pk_mul_f32 v[16:17], v[24:25], s[12:13] op_sel_hi:[1,0]
	s_nop 0
	v_cndmask_b32_e32 v27, v15, v14, vcc
	v_pk_mul_f32 v[14:15], v[22:23], s[12:13] op_sel_hi:[1,0]
	s_nop 0
	v_cvt_pk_f16_f32 v14, v14, v15
	v_cvt_pk_f16_f32 v15, v16, v17
	v_pk_mul_f32 v[16:17], v[18:19], s[12:13] op_sel_hi:[1,0]
	v_pk_mul_f32 v[18:19], v[20:21], s[12:13] op_sel_hi:[1,0]
	v_cvt_pk_f16_f32 v16, v16, v17
	v_cvt_pk_f16_f32 v17, v18, v19
	v_pk_mul_f32 v[18:19], v[64:65], s[12:13] op_sel_hi:[1,0]
	v_pk_mul_f32 v[20:21], v[60:61], s[12:13] op_sel_hi:[1,0]
	v_cvt_pk_f16_f32 v18, v18, v19
	v_cvt_pk_f16_f32 v19, v20, v21
	v_cvt_pk_f16_f32 v20, v10, v11
	v_pk_mul_f32 v[10:11], v[12:13], s[12:13] op_sel_hi:[1,0]
	v_add_u32_e32 v60, v72, v71
	v_cvt_pk_f16_f32 v21, v10, v11
	v_fma_f32 v10, v81, v26, -4.0
	v_mul_f32_e32 v22, 0xbfb8aa3b, v10
	ds_read_b128 v[10:13], v76
	ds_read_b128 v[62:65], v76 offset:2048
	ds_read_b128 v[82:85], v77
	ds_read_b128 v[86:89], v77 offset:2048
	ds_read_b64_tr_b16 v[90:91], v60 offset:32768
	ds_read_b64_tr_b16 v[92:93], v60 offset:34816
	ds_read_b64_tr_b16 v[94:95], v78 offset:32768
	ds_read_b64_tr_b16 v[96:97], v78 offset:34816
	ds_read_b64_tr_b16 v[98:99], v79 offset:32768
	ds_read_b64_tr_b16 v[100:101], v79 offset:34816
	ds_read_b64_tr_b16 v[102:103], v80 offset:32768
	ds_read_b64_tr_b16 v[104:105], v80 offset:34816
	v_fma_f32 v26, v81, v27, -4.0
	v_mul_f32_e32 v26, 0xbfb8aa3b, v26
	v_mov_b32_e32 v23, v22
	v_mov_b32_e32 v24, v22
	v_mov_b32_e32 v25, v22
	v_mov_b32_e32 v27, v26
	v_mov_b32_e32 v28, v26
	v_mov_b32_e32 v29, v26
	s_waitcnt lgkmcnt(11)
	v_mfma_f32_16x16x32_f16 v[106:109], v[10:13], v[6:9], v[22:25]
	v_mfma_f32_16x16x32_f16 v[10:13], v[10:13], v[14:17], v[26:29]
	s_waitcnt lgkmcnt(10)
	v_mfma_f32_16x16x32_f16 v[110:113], v[62:65], v[6:9], v[22:25]
	v_mfma_f32_16x16x32_f16 v[62:65], v[62:65], v[14:17], v[26:29]
	s_waitcnt lgkmcnt(9)
	v_mfma_f32_16x16x32_f16 v[106:109], v[82:85], v[2:5], v[106:109]
	v_mfma_f32_16x16x32_f16 v[82:85], v[82:85], v[18:21], v[10:13]
	s_waitcnt lgkmcnt(8)
	v_mfma_f32_16x16x32_f16 v[10:13], v[86:89], v[2:5], v[110:113]
	v_mfma_f32_16x16x32_f16 v[62:65], v[86:89], v[18:21], v[62:65]
	ds_read_b128 v[86:89], v77 offset:6144
	s_nop 0
	ds_read_b128 v[110:113], v77 offset:4096
	ds_read_b128 v[114:117], v76 offset:6144
	ds_read_b128 v[118:121], v76 offset:4096
	ds_read_b64_tr_b16 v[134:135], v60 offset:36864
	ds_read_b64_tr_b16 v[136:137], v60 offset:38912
	ds_read_b64_tr_b16 v[138:139], v78 offset:36864
	ds_read_b64_tr_b16 v[140:141], v78 offset:38912
	ds_read_b64_tr_b16 v[142:143], v79 offset:36864
	ds_read_b64_tr_b16 v[144:145], v79 offset:38912
	ds_read_b64_tr_b16 v[146:147], v80 offset:36864
	ds_read_b64_tr_b16 v[148:149], v80 offset:38912
	v_exp_f32_e32 v61, v106
	v_exp_f32_e32 v126, v62
	v_exp_f32_e32 v62, v107
	v_exp_f32_e32 v122, v10
	v_exp_f32_e32 v123, v11
	v_exp_f32_e32 v124, v12
	v_exp_f32_e32 v128, v84
	v_exp_f32_e32 v84, v13
	v_mov_b64_e32 v[12:13], s[6:7]
	v_exp_f32_e32 v82, v82
	v_exp_f32_e32 v83, v83
	v_exp_f32_e32 v127, v63
	v_exp_f32_e32 v63, v108
	v_exp_f32_e32 v129, v64
	v_exp_f32_e32 v64, v109
	v_mov_b64_e32 v[10:11], s[4:5]
	v_cvt_pk_f16_f32 v106, v61, v62
	v_exp_f32_e32 v61, v85
	v_exp_f32_e32 v65, v65
	v_cvt_pk_f16_f32 v107, v63, v64
	v_cvt_pk_f16_f32 v108, v122, v123
	v_cvt_pk_f16_f32 v109, v124, v84
	v_cvt_pk_f16_f32 v62, v82, v83
	v_cvt_pk_f16_f32 v63, v128, v61
	v_cvt_pk_f16_f32 v64, v126, v127
	v_cvt_pk_f16_f32 v65, v129, v65
	v_mfma_f32_16x16x32_f16 v[122:125], v[10:13], v[106:109], 0
	s_waitcnt lgkmcnt(14)
	v_mfma_f32_16x16x32_f16 v[82:85], v[90:93], v[106:109], 0
	v_mfma_f32_16x16x32_f16 v[90:93], v[90:93], v[62:65], 0
	v_mfma_f32_16x16x32_f16 v[126:129], v[94:97], v[106:109], 0
	v_mfma_f32_16x16x32_f16 v[94:97], v[94:97], v[62:65], 0
	v_mfma_f32_16x16x32_f16 v[130:133], v[98:101], v[106:109], 0
	v_mfma_f32_16x16x32_f16 v[98:101], v[98:101], v[62:65], 0
	s_waitcnt lgkmcnt(12)
	v_mfma_f32_16x16x32_f16 v[106:109], v[102:105], v[106:109], 0
	v_mfma_f32_16x16x32_f16 v[102:105], v[102:105], v[62:65], 0
	v_mfma_f32_16x16x32_f16 v[62:65], v[10:13], v[62:65], 0
	s_waitcnt lgkmcnt(8)
; #define LAS __attribute__((address_space(3)))
; template <bool CAUSAL, bool SHARED> ...
;     ...
;     for (int ks = 0; ks < nsteps; ++ks) {
;         LAS const unsigned char* va = Va + ks * 4096 + vrow; LAS const unsigned char* vb = Vb + ks * 4096 + vrow;
;         h16x4 fal[4], fah[4], fbl[4], fbh[4];
; #pragma unroll
;         for (int dt = 0; dt < 4; ++dt) { fal[dt] = vtr(va + ((dt ^ sw) << 5)); fah[dt] = vtr(va + 2048 + ((dt ^ sw) << 5));
;             if (!SHARED) { fbl[dt] = vtr(vb + ((dt ^ sw) << 5)); fbh[dt] = vtr(vb + 2048 + ((dt ^ sw) << 5)); } }
;         __builtin_amdgcn_sched_barrier(0);
;         f32x4 sa0, sa1, sb0, sb1;
;         sa0 = __builtin_amdgcn_mfma_f32_16x16x32_f16(ka[0], qa0, nma, 0, 0, 0); sb0 = __builtin_amdgcn_mfma_f32_16x16x32_f16(SHARED ? ka[0] : kb[0], qb0, nmb, 0, 0, 0);
;         sa1 = __builtin_amdgcn_mfma_f32_16x16x32_f16(ka[2], qa0, nma, 0, 0, 0); sb1 = __builtin_amdgcn_mfma_f32_16x16x32_f16(SHARED ? ka[2] : kb[2], qb0, nmb, 0, 0, 0);
;         sa0 = __builtin_amdgcn_mfma_f32_16x16x32_f16(ka[1], qa1, sa0, 0, 0, 0); sb0 = __builtin_amdgcn_mfma_f32_16x16x32_f16(SHARED ? ka[1] : kb[1], qb1, sb0, 0, 0, 0);
;         sa1 = __builtin_amdgcn_mfma_f32_16x16x32_f16(ka[3], qa1, sa1, 0, 0, 0); sb1 = __builtin_amdgcn_mfma_f32_16x16x32_f16(SHARED ? ka[3] : kb[3], qb1, sb1, 0, 0, 0);
;         __builtin_amdgcn_sched_barrier(0);
;         if (ks + 1 < nsteps) { LAS const unsigned char* kn = Ka + (ks + 1) * 4096;
;             ka[0] = *(LAS const h16x8*)(kn + kof0); ka[1] = *(LAS const h16x8*)(kn + kof1); ka[2] = *(LAS const h16x8*)(kn + 2048 + kof0); ka[3] = *(LAS const h16x8*)(kn + 2048 + kof1);
;             if (!SHARED) { LAS const unsigned char* kn2 = Kb + (ks + 1) * 4096;
;                 kb[0] = *(LAS const h16x8*)(kn2 + kof0); kb[1] = *(LAS const h16x8*)(kn2 + kof1); kb[2] = *(LAS const h16x8*)(kn2 + 2048 + kof0); kb[3] = *(LAS const h16x8*)(kn2 + 2048 + kof1); } }
;         __builtin_amdgcn_sched_barrier(0);
;         f32x4 pa0, pa1, pb0, pb1;
; #pragma unroll
;         for (int e = 0; e < 4; ++e) { pa0[e] = __builtin_amdgcn_exp2f(sa0[e]); pa1[e] = __builtin_amdgcn_exp2f(sa1[e]);
;                                       pb0[e] = __builtin_amdgcn_exp2f(sb0[e]); pb1[e] = __builtin_amdgcn_exp2f(sb1[e]); }
;         if (CAUSAL) { const int kr = ks * 32 + 4 * G;
; #pragma unroll
	v_mfma_f32_16x16x32_f16 v[150:153], v[118:121], v[6:9], v[22:25]
	v_mfma_f32_16x16x32_f16 v[118:121], v[118:121], v[14:17], v[26:29]
	v_mfma_f32_16x16x32_f16 v[154:157], v[114:117], v[6:9], v[22:25]
	v_mfma_f32_16x16x32_f16 v[114:117], v[114:117], v[14:17], v[26:29]
	v_mfma_f32_16x16x32_f16 v[150:153], v[110:113], v[2:5], v[150:153]
	v_mfma_f32_16x16x32_f16 v[110:113], v[110:113], v[18:21], v[118:121]
	v_mfma_f32_16x16x32_f16 v[118:121], v[86:89], v[2:5], v[154:157]
	v_mfma_f32_16x16x32_f16 v[86:89], v[86:89], v[18:21], v[114:117]
	s_nop 3
	ds_read_b128 v[114:117], v77 offset:10240
	ds_read_b128 v[154:157], v77 offset:8192
	ds_read_b128 v[158:161], v76 offset:10240
	ds_read_b128 v[162:165], v76 offset:8192
	v_exp_f32_e32 v61, v150
	v_exp_f32_e32 v166, v86
	v_exp_f32_e32 v86, v151
	v_exp_f32_e32 v150, v118
	v_exp_f32_e32 v110, v110
	v_exp_f32_e32 v151, v119
	v_exp_f32_e32 v111, v111
	v_exp_f32_e32 v167, v87
	v_exp_f32_e32 v87, v152
	v_exp_f32_e32 v152, v120
	v_exp_f32_e32 v112, v112
	v_exp_f32_e32 v119, v153
	v_exp_f32_e32 v153, v88
	v_exp_f32_e32 v88, v121
	v_cvt_pk_f16_f32 v118, v61, v86
	v_exp_f32_e32 v61, v113
	v_exp_f32_e32 v89, v89
	v_cvt_pk_f16_f32 v119, v87, v119
	v_cvt_pk_f16_f32 v120, v150, v151
	v_cvt_pk_f16_f32 v121, v152, v88
	v_cvt_pk_f16_f32 v86, v110, v111
	v_cvt_pk_f16_f32 v87, v112, v61
	v_cvt_pk_f16_f32 v88, v166, v167
	v_cvt_pk_f16_f32 v89, v153, v89
	v_mfma_f32_16x16x32_f16 v[122:125], v[10:13], v[118:121], v[122:125]
	s_waitcnt lgkmcnt(10)
	v_mfma_f32_16x16x32_f16 v[82:85], v[134:137], v[118:121], v[82:85]
	v_mfma_f32_16x16x32_f16 v[90:93], v[134:137], v[86:89], v[90:93]
	s_waitcnt lgkmcnt(8)
	v_mfma_f32_16x16x32_f16 v[110:113], v[138:141], v[118:121], v[126:129]
	v_mfma_f32_16x16x32_f16 v[94:97], v[138:141], v[86:89], v[94:97]
	s_waitcnt lgkmcnt(6)
	v_mfma_f32_16x16x32_f16 v[126:129], v[142:145], v[118:121], v[130:133]
	s_waitcnt lgkmcnt(4)
	v_mfma_f32_16x16x32_f16 v[106:109], v[146:149], v[118:121], v[106:109]
	ds_read_b64_tr_b16 v[118:119], v60 offset:40960
	ds_read_b64_tr_b16 v[120:121], v60 offset:43008
	ds_read_b64_tr_b16 v[130:131], v78 offset:40960
	ds_read_b64_tr_b16 v[132:133], v78 offset:43008
	ds_read_b64_tr_b16 v[134:135], v79 offset:40960
	ds_read_b64_tr_b16 v[136:137], v79 offset:43008
	ds_read_b64_tr_b16 v[138:139], v80 offset:40960
	ds_read_b64_tr_b16 v[140:141], v80 offset:43008
	v_mfma_f32_16x16x32_f16 v[98:101], v[142:145], v[86:89], v[98:101]
	v_mfma_f32_16x16x32_f16 v[102:105], v[146:149], v[86:89], v[102:105]
	v_mfma_f32_16x16x32_f16 v[62:65], v[10:13], v[86:89], v[62:65]
	s_waitcnt lgkmcnt(8)
	v_mfma_f32_16x16x32_f16 v[86:89], v[162:165], v[6:9], v[22:25]
	v_mfma_f32_16x16x32_f16 v[142:145], v[162:165], v[14:17], v[26:29]
	v_mfma_f32_16x16x32_f16 v[146:149], v[158:161], v[6:9], v[22:25]
	v_mfma_f32_16x16x32_f16 v[150:153], v[158:161], v[14:17], v[26:29]
	v_mfma_f32_16x16x32_f16 v[86:89], v[154:157], v[2:5], v[86:89]
	v_mfma_f32_16x16x32_f16 v[142:145], v[154:157], v[18:21], v[142:145]
	v_mfma_f32_16x16x32_f16 v[146:149], v[114:117], v[2:5], v[146:149]
	v_mfma_f32_16x16x32_f16 v[114:117], v[114:117], v[18:21], v[150:153]
	s_nop 3
	ds_read_b128 v[150:153], v77 offset:14336
	ds_read_b128 v[154:157], v77 offset:12288
	ds_read_b128 v[158:161], v76 offset:14336
	ds_read_b128 v[162:165], v76 offset:12288
	v_exp_f32_e32 v61, v86
	v_exp_f32_e32 v86, v87
	v_exp_f32_e32 v146, v146
	v_exp_f32_e32 v142, v142
	v_exp_f32_e32 v166, v114
	v_exp_f32_e32 v114, v147
	v_exp_f32_e32 v143, v143
	v_exp_f32_e32 v147, v115
	v_exp_f32_e32 v87, v88
	v_exp_f32_e32 v115, v148
	v_exp_f32_e32 v144, v144
	v_exp_f32_e32 v88, v89
	v_exp_f32_e32 v148, v116
	v_exp_f32_e32 v89, v149
	v_cvt_pk_f16_f32 v86, v61, v86
	v_exp_f32_e32 v61, v145
	v_exp_f32_e32 v117, v117
	v_cvt_pk_f16_f32 v87, v87, v88
	v_cvt_pk_f16_f32 v88, v146, v114
	v_cvt_pk_f16_f32 v89, v115, v89
	v_cvt_pk_f16_f32 v114, v142, v143
	v_cvt_pk_f16_f32 v115, v144, v61
	v_cvt_pk_f16_f32 v116, v166, v147
	v_cvt_pk_f16_f32 v117, v148, v117
	v_mfma_f32_16x16x32_f16 v[122:125], v[10:13], v[86:89], v[122:125]
	s_waitcnt lgkmcnt(10)
	v_mfma_f32_16x16x32_f16 v[82:85], v[118:121], v[86:89], v[82:85]
	v_mfma_f32_16x16x32_f16 v[90:93], v[118:121], v[114:117], v[90:93]
	s_waitcnt lgkmcnt(8)
	v_mfma_f32_16x16x32_f16 v[110:113], v[130:133], v[86:89], v[110:113]
	v_mfma_f32_16x16x32_f16 v[94:97], v[130:133], v[114:117], v[94:97]
	s_waitcnt lgkmcnt(6)
	v_mfma_f32_16x16x32_f16 v[118:121], v[134:137], v[86:89], v[126:129]
	v_mfma_f32_16x16x32_f16 v[98:101], v[134:137], v[114:117], v[98:101]
	s_waitcnt lgkmcnt(4)
	v_mfma_f32_16x16x32_f16 v[86:89], v[138:141], v[86:89], v[106:109]
	s_nop 2
	ds_read_b64_tr_b16 v[106:107], v60 offset:45056
	ds_read_b64_tr_b16 v[108:109], v60 offset:47104
	ds_read_b64_tr_b16 v[126:127], v78 offset:45056
	ds_read_b64_tr_b16 v[128:129], v78 offset:47104
	ds_read_b64_tr_b16 v[130:131], v79 offset:45056
	ds_read_b64_tr_b16 v[132:133], v79 offset:47104
	ds_read_b64_tr_b16 v[134:135], v80 offset:45056
	ds_read_b64_tr_b16 v[136:137], v80 offset:47104
	v_mfma_f32_16x16x32_f16 v[102:105], v[138:141], v[114:117], v[102:105]
	v_mfma_f32_16x16x32_f16 v[62:65], v[10:13], v[114:117], v[62:65]
	s_waitcnt lgkmcnt(8)
; #define LAS __attribute__((address_space(3)))
; template <bool CAUSAL, bool SHARED> ...
;     ...
;     for (int ks = 0; ks < nsteps; ++ks) {
;         LAS const unsigned char* va = Va + ks * 4096 + vrow; LAS const unsigned char* vb = Vb + ks * 4096 + vrow;
;         h16x4 fal[4], fah[4], fbl[4], fbh[4];
; #pragma unroll
;         for (int dt = 0; dt < 4; ++dt) { fal[dt] = vtr(va + ((dt ^ sw) << 5)); fah[dt] = vtr(va + 2048 + ((dt ^ sw) << 5));
;             if (!SHARED) { fbl[dt] = vtr(vb + ((dt ^ sw) << 5)); fbh[dt] = vtr(vb + 2048 + ((dt ^ sw) << 5)); } }
;         __builtin_amdgcn_sched_barrier(0);
;         f32x4 sa0, sa1, sb0, sb1;
;         sa0 = __builtin_amdgcn_mfma_f32_16x16x32_f16(ka[0], qa0, nma, 0, 0, 0); sb0 = __builtin_amdgcn_mfma_f32_16x16x32_f16(SHARED ? ka[0] : kb[0], qb0, nmb, 0, 0, 0);
;         sa1 = __builtin_amdgcn_mfma_f32_16x16x32_f16(ka[2], qa0, nma, 0, 0, 0); sb1 = __builtin_amdgcn_mfma_f32_16x16x32_f16(SHARED ? ka[2] : kb[2], qb0, nmb, 0, 0, 0);
;         sa0 = __builtin_amdgcn_mfma_f32_16x16x32_f16(ka[1], qa1, sa0, 0, 0, 0); sb0 = __builtin_amdgcn_mfma_f32_16x16x32_f16(SHARED ? ka[1] : kb[1], qb1, sb0, 0, 0, 0);
;         sa1 = __builtin_amdgcn_mfma_f32_16x16x32_f16(ka[3], qa1, sa1, 0, 0, 0); sb1 = __builtin_amdgcn_mfma_f32_16x16x32_f16(SHARED ? ka[3] : kb[3], qb1, sb1, 0, 0, 0);
;         __builtin_amdgcn_sched_barrier(0);
;         if (ks + 1 < nsteps) { LAS const unsigned char* kn = Ka + (ks + 1) * 4096;
;             ka[0] = *(LAS const h16x8*)(kn + kof0); ka[1] = *(LAS const h16x8*)(kn + kof1); ka[2] = *(LAS const h16x8*)(kn + 2048 + kof0); ka[3] = *(LAS const h16x8*)(kn + 2048 + kof1);
;             if (!SHARED) { LAS const unsigned char* kn2 = Kb + (ks + 1) * 4096;
;                 kb[0] = *(LAS const h16x8*)(kn2 + kof0); kb[1] = *(LAS const h16x8*)(kn2 + kof1); kb[2] = *(LAS const h16x8*)(kn2 + 2048 + kof0); kb[3] = *(LAS const h16x8*)(kn2 + 2048 + kof1); } }
;         __builtin_amdgcn_sched_barrier(0);
;         f32x4 pa0, pa1, pb0, pb1;
; #pragma unroll
;         for (int e = 0; e < 4; ++e) { pa0[e] = __builtin_amdgcn_exp2f(sa0[e]); pa1[e] = __builtin_amdgcn_exp2f(sa1[e]);
;                                       pb0[e] = __builtin_amdgcn_exp2f(sb0[e]); pb1[e] = __builtin_amdgcn_exp2f(sb1[e]); }
;         if (CAUSAL) { const int kr = ks * 32 + 4 * G;
; #pragma unroll
	v_mfma_f32_16x16x32_f16 v[114:117], v[162:165], v[6:9], v[22:25]
	v_mfma_f32_16x16x32_f16 v[138:141], v[162:165], v[14:17], v[26:29]
	v_mfma_f32_16x16x32_f16 v[142:145], v[158:161], v[6:9], v[22:25]
	v_mfma_f32_16x16x32_f16 v[146:149], v[158:161], v[14:17], v[26:29]
	v_mfma_f32_16x16x32_f16 v[114:117], v[154:157], v[2:5], v[114:117]
	v_mfma_f32_16x16x32_f16 v[138:141], v[154:157], v[18:21], v[138:141]
	v_mfma_f32_16x16x32_f16 v[142:145], v[150:153], v[2:5], v[142:145]
	v_mfma_f32_16x16x32_f16 v[146:149], v[150:153], v[18:21], v[146:149]
	ds_read_b128 v[150:153], v77 offset:18432
	ds_read_b128 v[154:157], v77 offset:16384
	ds_read_b128 v[158:161], v76 offset:18432
	ds_read_b128 v[162:165], v76 offset:16384
	s_nop 0
	v_exp_f32_e32 v61, v114
	v_exp_f32_e32 v114, v115
	v_exp_f32_e32 v142, v142
	v_exp_f32_e32 v138, v138
	v_exp_f32_e32 v146, v146
	v_exp_f32_e32 v143, v143
	v_exp_f32_e32 v139, v139
	v_exp_f32_e32 v147, v147
	v_exp_f32_e32 v115, v116
	v_exp_f32_e32 v144, v144
	v_exp_f32_e32 v140, v140
	v_exp_f32_e32 v116, v117
	v_exp_f32_e32 v148, v148
	v_exp_f32_e32 v117, v145
	v_cvt_pk_f16_f32 v114, v61, v114
	v_exp_f32_e32 v61, v141
	v_exp_f32_e32 v141, v149
	v_cvt_pk_f16_f32 v115, v115, v116
	v_cvt_pk_f16_f32 v116, v142, v143
	v_cvt_pk_f16_f32 v117, v144, v117
	v_cvt_pk_f16_f32 v138, v138, v139
	v_cvt_pk_f16_f32 v139, v140, v61
	v_cvt_pk_f16_f32 v140, v146, v147
	v_cvt_pk_f16_f32 v141, v148, v141
	v_mfma_f32_16x16x32_f16 v[122:125], v[10:13], v[114:117], v[122:125]
	s_waitcnt lgkmcnt(10)
	v_mfma_f32_16x16x32_f16 v[82:85], v[106:109], v[114:117], v[82:85]
	v_mfma_f32_16x16x32_f16 v[90:93], v[106:109], v[138:141], v[90:93]
	s_waitcnt lgkmcnt(8)
	v_mfma_f32_16x16x32_f16 v[106:109], v[126:129], v[114:117], v[110:113]
	v_mfma_f32_16x16x32_f16 v[94:97], v[126:129], v[138:141], v[94:97]
	s_waitcnt lgkmcnt(6)
	v_mfma_f32_16x16x32_f16 v[110:113], v[130:133], v[114:117], v[118:121]
	v_mfma_f32_16x16x32_f16 v[98:101], v[130:133], v[138:141], v[98:101]
	s_waitcnt lgkmcnt(4)
	v_mfma_f32_16x16x32_f16 v[86:89], v[134:137], v[114:117], v[86:89]
	ds_read_b64_tr_b16 v[114:115], v60 offset:49152
	ds_read_b64_tr_b16 v[116:117], v60 offset:51200
	ds_read_b64_tr_b16 v[118:119], v78 offset:49152
	ds_read_b64_tr_b16 v[120:121], v78 offset:51200
	ds_read_b64_tr_b16 v[126:127], v79 offset:49152
	ds_read_b64_tr_b16 v[128:129], v79 offset:51200
	ds_read_b64_tr_b16 v[130:131], v80 offset:49152
	ds_read_b64_tr_b16 v[132:133], v80 offset:51200
	v_mfma_f32_16x16x32_f16 v[102:105], v[134:137], v[138:141], v[102:105]
	v_mfma_f32_16x16x32_f16 v[62:65], v[10:13], v[138:141], v[62:65]
	s_waitcnt lgkmcnt(8)
	v_mfma_f32_16x16x32_f16 v[134:137], v[162:165], v[6:9], v[22:25]
	v_mfma_f32_16x16x32_f16 v[138:141], v[162:165], v[14:17], v[26:29]
	v_mfma_f32_16x16x32_f16 v[142:145], v[158:161], v[6:9], v[22:25]
	v_mfma_f32_16x16x32_f16 v[146:149], v[158:161], v[14:17], v[26:29]
	v_mfma_f32_16x16x32_f16 v[134:137], v[154:157], v[2:5], v[134:137]
	v_mfma_f32_16x16x32_f16 v[138:141], v[154:157], v[18:21], v[138:141]
	v_mfma_f32_16x16x32_f16 v[142:145], v[150:153], v[2:5], v[142:145]
	v_mfma_f32_16x16x32_f16 v[146:149], v[150:153], v[18:21], v[146:149]
	ds_read_b128 v[150:153], v77 offset:22528
	ds_read_b128 v[154:157], v77 offset:20480
	ds_read_b128 v[158:161], v76 offset:22528
	ds_read_b128 v[162:165], v76 offset:20480
	s_nop 0
	v_exp_f32_e32 v61, v134
	v_exp_f32_e32 v134, v135
	v_exp_f32_e32 v142, v142
	v_exp_f32_e32 v138, v138
	v_exp_f32_e32 v146, v146
	v_exp_f32_e32 v143, v143
	v_exp_f32_e32 v139, v139
	v_exp_f32_e32 v147, v147
	v_exp_f32_e32 v135, v136
	v_exp_f32_e32 v144, v144
	v_exp_f32_e32 v140, v140
	v_exp_f32_e32 v136, v137
	v_exp_f32_e32 v148, v148
	v_exp_f32_e32 v137, v145
	v_cvt_pk_f16_f32 v134, v61, v134
	v_exp_f32_e32 v61, v141
	v_exp_f32_e32 v141, v149
	v_cvt_pk_f16_f32 v135, v135, v136
	v_cvt_pk_f16_f32 v136, v142, v143
	v_cvt_pk_f16_f32 v137, v144, v137
	v_cvt_pk_f16_f32 v138, v138, v139
	v_cvt_pk_f16_f32 v139, v140, v61
	v_cvt_pk_f16_f32 v140, v146, v147
	v_cvt_pk_f16_f32 v141, v148, v141
	s_waitcnt lgkmcnt(10)
	v_mfma_f32_16x16x32_f16 v[82:85], v[114:117], v[134:137], v[82:85]
	v_mfma_f32_16x16x32_f16 v[90:93], v[114:117], v[138:141], v[90:93]
	s_waitcnt lgkmcnt(8)
	v_mfma_f32_16x16x32_f16 v[106:109], v[118:121], v[134:137], v[106:109]
	v_mfma_f32_16x16x32_f16 v[94:97], v[118:121], v[138:141], v[94:97]
	s_waitcnt lgkmcnt(6)
	v_mfma_f32_16x16x32_f16 v[110:113], v[126:129], v[134:137], v[110:113]
	v_mfma_f32_16x16x32_f16 v[98:101], v[126:129], v[138:141], v[98:101]
	s_waitcnt lgkmcnt(4)
	v_mfma_f32_16x16x32_f16 v[86:89], v[130:133], v[134:137], v[86:89]
	v_mfma_f32_16x16x32_f16 v[102:105], v[130:133], v[138:141], v[102:105]
	ds_read_b64_tr_b16 v[114:115], v60 offset:53248
	ds_read_b64_tr_b16 v[116:117], v60 offset:55296
	ds_read_b64_tr_b16 v[118:119], v78 offset:53248
	ds_read_b64_tr_b16 v[120:121], v78 offset:55296
	ds_read_b64_tr_b16 v[126:127], v79 offset:53248
	ds_read_b64_tr_b16 v[128:129], v79 offset:55296
	ds_read_b64_tr_b16 v[130:131], v80 offset:53248
	ds_read_b64_tr_b16 v[132:133], v80 offset:55296
	v_mfma_f32_16x16x32_f16 v[122:125], v[10:13], v[134:137], v[122:125]
	v_mfma_f32_16x16x32_f16 v[62:65], v[10:13], v[138:141], v[62:65]
	s_waitcnt lgkmcnt(8)
; #define LAS __attribute__((address_space(3)))
; template <bool CAUSAL, bool SHARED> ...
;     ...
;     for (int ks = 0; ks < nsteps; ++ks) {
;         LAS const unsigned char* va = Va + ks * 4096 + vrow; LAS const unsigned char* vb = Vb + ks * 4096 + vrow;
;         h16x4 fal[4], fah[4], fbl[4], fbh[4];
; #pragma unroll
;         for (int dt = 0; dt < 4; ++dt) { fal[dt] = vtr(va + ((dt ^ sw) << 5)); fah[dt] = vtr(va + 2048 + ((dt ^ sw) << 5));
;             if (!SHARED) { fbl[dt] = vtr(vb + ((dt ^ sw) << 5)); fbh[dt] = vtr(vb + 2048 + ((dt ^ sw) << 5)); } }
;         __builtin_amdgcn_sched_barrier(0);
;         f32x4 sa0, sa1, sb0, sb1;
;         sa0 = __builtin_amdgcn_mfma_f32_16x16x32_f16(ka[0], qa0, nma, 0, 0, 0); sb0 = __builtin_amdgcn_mfma_f32_16x16x32_f16(SHARED ? ka[0] : kb[0], qb0, nmb, 0, 0, 0);
;         sa1 = __builtin_amdgcn_mfma_f32_16x16x32_f16(ka[2], qa0, nma, 0, 0, 0); sb1 = __builtin_amdgcn_mfma_f32_16x16x32_f16(SHARED ? ka[2] : kb[2], qb0, nmb, 0, 0, 0);
;         sa0 = __builtin_amdgcn_mfma_f32_16x16x32_f16(ka[1], qa1, sa0, 0, 0, 0); sb0 = __builtin_amdgcn_mfma_f32_16x16x32_f16(SHARED ? ka[1] : kb[1], qb1, sb0, 0, 0, 0);
;         sa1 = __builtin_amdgcn_mfma_f32_16x16x32_f16(ka[3], qa1, sa1, 0, 0, 0); sb1 = __builtin_amdgcn_mfma_f32_16x16x32_f16(SHARED ? ka[3] : kb[3], qb1, sb1, 0, 0, 0);
;         __builtin_amdgcn_sched_barrier(0);
;         if (ks + 1 < nsteps) { LAS const unsigned char* kn = Ka + (ks + 1) * 4096;
;             ka[0] = *(LAS const h16x8*)(kn + kof0); ka[1] = *(LAS const h16x8*)(kn + kof1); ka[2] = *(LAS const h16x8*)(kn + 2048 + kof0); ka[3] = *(LAS const h16x8*)(kn + 2048 + kof1);
;             if (!SHARED) { LAS const unsigned char* kn2 = Kb + (ks + 1) * 4096;
;                 kb[0] = *(LAS const h16x8*)(kn2 + kof0); kb[1] = *(LAS const h16x8*)(kn2 + kof1); kb[2] = *(LAS const h16x8*)(kn2 + 2048 + kof0); kb[3] = *(LAS const h16x8*)(kn2 + 2048 + kof1); } }
;         __builtin_amdgcn_sched_barrier(0);
;         f32x4 pa0, pa1, pb0, pb1;
; #pragma unroll
;         for (int e = 0; e < 4; ++e) { pa0[e] = __builtin_amdgcn_exp2f(sa0[e]); pa1[e] = __builtin_amdgcn_exp2f(sa1[e]);
;                                       pb0[e] = __builtin_amdgcn_exp2f(sb0[e]); pb1[e] = __builtin_amdgcn_exp2f(sb1[e]); }
;         if (CAUSAL) { const int kr = ks * 32 + 4 * G;
; #pragma unroll
	v_mfma_f32_16x16x32_f16 v[134:137], v[162:165], v[6:9], v[22:25]
	v_mfma_f32_16x16x32_f16 v[138:141], v[162:165], v[14:17], v[26:29]
	v_mfma_f32_16x16x32_f16 v[142:145], v[158:161], v[6:9], v[22:25]
	v_mfma_f32_16x16x32_f16 v[146:149], v[158:161], v[14:17], v[26:29]
	v_mfma_f32_16x16x32_f16 v[134:137], v[154:157], v[2:5], v[134:137]
	v_mfma_f32_16x16x32_f16 v[138:141], v[154:157], v[18:21], v[138:141]
	v_mfma_f32_16x16x32_f16 v[142:145], v[150:153], v[2:5], v[142:145]
	v_mfma_f32_16x16x32_f16 v[146:149], v[150:153], v[18:21], v[146:149]
	ds_read_b128 v[150:153], v77 offset:26624
	ds_read_b128 v[154:157], v77 offset:24576
	ds_read_b128 v[158:161], v76 offset:26624
	ds_read_b128 v[162:165], v76 offset:24576
	s_nop 0
	v_exp_f32_e32 v61, v134
	v_exp_f32_e32 v134, v135
	v_exp_f32_e32 v142, v142
	v_exp_f32_e32 v138, v138
	v_exp_f32_e32 v146, v146
	v_exp_f32_e32 v143, v143
	v_exp_f32_e32 v139, v139
	v_exp_f32_e32 v147, v147
	v_exp_f32_e32 v135, v136
	v_exp_f32_e32 v144, v144
	v_exp_f32_e32 v140, v140
	v_exp_f32_e32 v136, v137
	v_exp_f32_e32 v148, v148
	v_exp_f32_e32 v137, v145
	v_cvt_pk_f16_f32 v134, v61, v134
	v_exp_f32_e32 v61, v141
	v_exp_f32_e32 v141, v149
	v_cvt_pk_f16_f32 v135, v135, v136
	v_cvt_pk_f16_f32 v136, v142, v143
	v_cvt_pk_f16_f32 v137, v144, v137
	v_cvt_pk_f16_f32 v138, v138, v139
	v_cvt_pk_f16_f32 v139, v140, v61
	v_cvt_pk_f16_f32 v140, v146, v147
	v_cvt_pk_f16_f32 v141, v148, v141
	s_waitcnt lgkmcnt(10)
	v_mfma_f32_16x16x32_f16 v[82:85], v[114:117], v[134:137], v[82:85]
	v_mfma_f32_16x16x32_f16 v[90:93], v[114:117], v[138:141], v[90:93]
	s_waitcnt lgkmcnt(8)
	v_mfma_f32_16x16x32_f16 v[106:109], v[118:121], v[134:137], v[106:109]
	v_mfma_f32_16x16x32_f16 v[94:97], v[118:121], v[138:141], v[94:97]
	s_waitcnt lgkmcnt(6)
	v_mfma_f32_16x16x32_f16 v[110:113], v[126:129], v[134:137], v[110:113]
	v_mfma_f32_16x16x32_f16 v[98:101], v[126:129], v[138:141], v[98:101]
	s_waitcnt lgkmcnt(4)
	v_mfma_f32_16x16x32_f16 v[86:89], v[130:133], v[134:137], v[86:89]
	v_mfma_f32_16x16x32_f16 v[102:105], v[130:133], v[138:141], v[102:105]
	ds_read_b64_tr_b16 v[114:115], v60 offset:57344
	ds_read_b64_tr_b16 v[116:117], v60 offset:59392
	ds_read_b64_tr_b16 v[118:119], v78 offset:57344
	ds_read_b64_tr_b16 v[120:121], v78 offset:59392
	ds_read_b64_tr_b16 v[126:127], v79 offset:57344
	ds_read_b64_tr_b16 v[128:129], v79 offset:59392
	ds_read_b64_tr_b16 v[130:131], v80 offset:57344
	ds_read_b64_tr_b16 v[132:133], v80 offset:59392
	v_mfma_f32_16x16x32_f16 v[122:125], v[10:13], v[134:137], v[122:125]
	v_mfma_f32_16x16x32_f16 v[62:65], v[10:13], v[138:141], v[62:65]
	s_waitcnt lgkmcnt(8)
	v_mfma_f32_16x16x32_f16 v[134:137], v[162:165], v[6:9], v[22:25]
	v_mfma_f32_16x16x32_f16 v[138:141], v[162:165], v[14:17], v[26:29]
	v_mfma_f32_16x16x32_f16 v[142:145], v[158:161], v[6:9], v[22:25]
	v_mfma_f32_16x16x32_f16 v[146:149], v[158:161], v[14:17], v[26:29]
	v_mfma_f32_16x16x32_f16 v[134:137], v[154:157], v[2:5], v[134:137]
	v_mfma_f32_16x16x32_f16 v[138:141], v[154:157], v[18:21], v[138:141]
	v_mfma_f32_16x16x32_f16 v[142:145], v[150:153], v[2:5], v[142:145]
	v_mfma_f32_16x16x32_f16 v[146:149], v[150:153], v[18:21], v[146:149]
	ds_read_b128 v[150:153], v77 offset:30720
	ds_read_b128 v[154:157], v77 offset:28672
	ds_read_b128 v[158:161], v76 offset:30720
	ds_read_b128 v[162:165], v76 offset:28672
	s_nop 0
	v_exp_f32_e32 v61, v134
	v_exp_f32_e32 v134, v135
	v_exp_f32_e32 v142, v142
	v_exp_f32_e32 v138, v138
	v_exp_f32_e32 v146, v146
	v_exp_f32_e32 v143, v143
	v_exp_f32_e32 v139, v139
	v_exp_f32_e32 v147, v147
	v_exp_f32_e32 v135, v136
	v_exp_f32_e32 v144, v144
	v_exp_f32_e32 v140, v140
	v_exp_f32_e32 v136, v137
	v_exp_f32_e32 v148, v148
	v_exp_f32_e32 v137, v145
	v_cvt_pk_f16_f32 v134, v61, v134
	v_exp_f32_e32 v61, v141
	v_exp_f32_e32 v141, v149
	v_cvt_pk_f16_f32 v135, v135, v136
	v_cvt_pk_f16_f32 v136, v142, v143
	v_cvt_pk_f16_f32 v137, v144, v137
	v_cvt_pk_f16_f32 v138, v138, v139
	v_cvt_pk_f16_f32 v139, v140, v61
	v_cvt_pk_f16_f32 v140, v146, v147
	v_cvt_pk_f16_f32 v141, v148, v141
	s_waitcnt lgkmcnt(10)
	v_mfma_f32_16x16x32_f16 v[82:85], v[114:117], v[134:137], v[82:85]
	v_mfma_f32_16x16x32_f16 v[90:93], v[114:117], v[138:141], v[90:93]
	s_waitcnt lgkmcnt(8)
	v_mfma_f32_16x16x32_f16 v[106:109], v[118:121], v[134:137], v[106:109]
	v_mfma_f32_16x16x32_f16 v[94:97], v[118:121], v[138:141], v[94:97]
	s_waitcnt lgkmcnt(6)
	v_mfma_f32_16x16x32_f16 v[110:113], v[126:129], v[134:137], v[110:113]
	v_mfma_f32_16x16x32_f16 v[98:101], v[126:129], v[138:141], v[98:101]
	s_waitcnt lgkmcnt(4)
	v_mfma_f32_16x16x32_f16 v[86:89], v[130:133], v[134:137], v[86:89]
	v_mfma_f32_16x16x32_f16 v[102:105], v[130:133], v[138:141], v[102:105]
	ds_read_b64_tr_b16 v[114:115], v60 offset:61440
	ds_read_b64_tr_b16 v[116:117], v60 offset:63488
	ds_read_b64_tr_b16 v[118:119], v78 offset:61440
	ds_read_b64_tr_b16 v[120:121], v78 offset:63488
	ds_read_b64_tr_b16 v[126:127], v79 offset:61440
	ds_read_b64_tr_b16 v[128:129], v79 offset:63488
	ds_read_b64_tr_b16 v[130:131], v80 offset:61440
	ds_read_b64_tr_b16 v[132:133], v80 offset:63488
	v_mfma_f32_16x16x32_f16 v[122:125], v[10:13], v[134:137], v[122:125]
	v_mfma_f32_16x16x32_f16 v[60:63], v[10:13], v[138:141], v[62:65]
	s_waitcnt lgkmcnt(8)
; __device__ __forceinline__ unsigned pk8(float a, float b, float c, float d) { int w = __builtin_amdgcn_cvt_pk_fp8_f32(a, b, 0, false); w = __builtin_amdgcn_cvt_pk_fp8_f32(c, d, w, true); return (unsigned)w; }
; __device__ __forceinline__ int pair16_dim(int G, int dt0) { return (G & 1) ? 16 * (dt0 + 1) + 4 * (G - 1) : 16 * dt0 + 4 * G; }
; __device__ __forceinline__ void store_o8(unsigned char* rowp, const f32x4 (&o)[4], float il, int G) {
;     const float c = il * F8_SY;
; #pragma unroll
;     for (int pr = 0; pr < 2; ++pr) { const int dt0 = 2 * pr;
;         const unsigned a = pk8(o[dt0][0] * c, o[dt0][1] * c, o[dt0][2] * c, o[dt0][3] * c), b = pk8(o[dt0 + 1][0] * c, o[dt0 + 1][1] * c, o[dt0 + 1][2] * c, o[dt0 + 1][3] * c);
;         const auto r = __builtin_amdgcn_permlane16_swap(a, b, false, false);
;         *(u32x2*)(rowp + pair16_dim(G, dt0)) = (u32x2){r[0], r[1]}; }
; }
; template <bool Y8>
; __device__ __forceinline__ void xattn_chunk(const Frame& F, const Args& a, int chunk, const f16_t* P, int ldp, int qcol0, const float* gqm, f16_t* Y) {
;     ...
;         const float ila = 1.0f / lsa, ilb = 1.0f / lsb;
;         if constexpr (Y8) { unsigned char* yp = (unsigned char*)Y + MIXW + head * HD; store_o8(yp + (size_t)rowa * DM, oa, ila, G); store_o8(yp + (size_t)rowb * DM, ob, ilb, G); }
;         else { f16_t* yp = Y + MIXW + head * HD; store_o16(yp + (size_t)rowa * DM, oa, ila, G); store_o16(yp + (size_t)rowb * DM, ob, ilb, G); }
;         __syncthreads();
;     }
	v_mfma_f32_16x16x32_f16 v[134:137], v[162:165], v[6:9], v[22:25]
	v_mfma_f32_16x16x32_f16 v[138:141], v[162:165], v[14:17], v[26:29]
	v_mfma_f32_16x16x32_f16 v[6:9], v[158:161], v[6:9], v[22:25]
	v_mfma_f32_16x16x32_f16 v[14:17], v[158:161], v[14:17], v[26:29]
	v_mfma_f32_16x16x32_f16 v[22:25], v[154:157], v[2:5], v[134:137]
	v_mfma_f32_16x16x32_f16 v[26:29], v[154:157], v[18:21], v[138:141]
	v_mfma_f32_16x16x32_f16 v[2:5], v[150:153], v[2:5], v[6:9]
	v_mfma_f32_16x16x32_f16 v[6:9], v[150:153], v[18:21], v[14:17]
	s_nop 7
	v_exp_f32_e32 v21, v7
	v_exp_f32_e32 v7, v4
	v_exp_f32_e32 v5, v5
	v_exp_f32_e32 v14, v22
	v_exp_f32_e32 v15, v2
	v_exp_f32_e32 v20, v6
	v_exp_f32_e32 v2, v23
	v_exp_f32_e32 v6, v3
	v_exp_f32_e32 v3, v24
	v_exp_f32_e32 v4, v25
	v_exp_f32_e32 v18, v26
	v_exp_f32_e32 v19, v27
	v_exp_f32_e32 v22, v28
	v_exp_f32_e32 v23, v8
	v_cvt_pk_f16_f32 v5, v7, v5
	v_exp_f32_e32 v7, v29
	v_exp_f32_e32 v9, v9
	v_cvt_pk_f16_f32 v2, v14, v2
	v_cvt_pk_f16_f32 v3, v3, v4
	v_cvt_pk_f16_f32 v4, v15, v6
	v_cvt_pk_f16_f32 v6, v18, v19
	v_cvt_pk_f16_f32 v7, v22, v7
	v_mfma_f32_16x16x32_f16 v[14:17], v[10:13], v[2:5], v[122:125]
	v_cvt_pk_f16_f32 v8, v20, v21
	v_cvt_pk_f16_f32 v9, v23, v9
	s_add_u32 s2, s13, s42
	s_waitcnt lgkmcnt(6)
	v_mfma_f32_16x16x32_f16 v[16:19], v[114:117], v[2:5], v[82:85]
	s_addc_u32 s3, s16, 0
	v_mov_b32_e32 v28, 0
	v_mov_b32_e32 v29, 0
	v_mfma_f32_16x16x32_f16 v[20:23], v[114:117], v[6:9], v[90:93]
	v_mov_b32_e32 v65, 0
	v_mov_b32_e32 v64, 0
	s_and_b64 s[0:1], exec, s[14:15]
	s_waitcnt lgkmcnt(4)
	v_mfma_f32_16x16x32_f16 v[24:27], v[118:121], v[2:5], v[106:109]
	s_mov_b32 s8, 1
	s_mov_b64 s[14:15], 0
	v_mfma_f32_16x16x32_f16 v[82:85], v[118:121], v[6:9], v[94:97]
	v_mov_b32_e32 v106, 0
	v_mov_b32_e32 v107, 0
	v_mov_b32_e32 v108, 0
	s_waitcnt lgkmcnt(2)
	v_mfma_f32_16x16x32_f16 v[90:93], v[126:129], v[2:5], v[110:113]
	v_mov_b32_e32 v109, 0
	v_mfma_f32_16x16x32_f16 v[94:97], v[126:129], v[6:9], v[98:101]
	s_waitcnt lgkmcnt(0)
	v_mfma_f32_16x16x32_f16 v[2:5], v[130:133], v[2:5], v[86:89]
	s_nop 0
	v_lshl_add_u64 v[98:99], s[2:3], 0, v[52:53]
	v_lshl_add_u64 v[100:101], s[2:3], 0, v[56:57]
	v_lshl_add_u64 v[98:99], v[98:99], 0, v[30:31]
	v_mfma_f32_16x16x32_f16 v[86:89], v[130:133], v[6:9], v[102:105]
	v_lshl_add_u64 v[100:101], v[100:101], 0, v[30:31]
	v_mfma_f32_16x16x32_f16 v[6:9], v[10:13], v[6:9], v[60:63]
	s_nop 7
	v_div_scale_f32 v7, s[2:3], v14, v14, 1.0
	v_div_scale_f32 v9, s[2:3], v6, v6, 1.0
	v_rcp_f32_e32 v11, v7
	v_rcp_f32_e32 v12, v9
	v_div_scale_f32 v8, vcc, 1.0, v14, 1.0
	v_fma_f32 v13, -v7, v11, 1.0
	v_fma_f32 v15, -v9, v12, 1.0
	v_fmac_f32_e32 v11, v13, v11
	v_div_scale_f32 v10, s[2:3], 1.0, v6, 1.0
	v_fmac_f32_e32 v12, v15, v12
	v_mul_f32_e32 v13, v8, v11
	v_mul_f32_e32 v15, v10, v12
	v_fma_f32 v60, -v7, v13, v8
	v_fma_f32 v61, -v9, v15, v10
	v_fmac_f32_e32 v13, v60, v11
	v_fmac_f32_e32 v15, v61, v12
	v_fma_f32 v7, -v7, v13, v8
	v_fma_f32 v8, -v9, v15, v10
	v_div_fmas_f32 v7, v7, v11, v13
	s_mov_b64 vcc, s[2:3]
	v_div_fixup_f32 v7, v7, v14, 1.0
	v_div_fmas_f32 v8, v8, v12, v15
	v_div_fixup_f32 v6, v8, v6, 1.0
	v_mul_f32_e32 v7, 0x42000000, v7
	v_mul_f32_e32 v8, v16, v7
	v_mul_f32_e32 v9, v17, v7
	v_mul_f32_e32 v12, v7, v24
	v_mul_f32_e32 v13, v7, v25
	v_mul_f32_e32 v2, v7, v2
	v_mul_f32_e32 v3, v7, v3
	v_mul_f32_e32 v6, 0x42000000, v6
	v_mul_f32_e32 v16, v7, v90
	v_mul_f32_e32 v17, v7, v91
	v_cvt_pk_fp8_f32 v28, v8, v9
	v_cvt_pk_fp8_f32 v29, v12, v13
	v_cvt_pk_fp8_f32 v65, v2, v3
	v_mul_f32_e32 v2, v20, v6
	v_mul_f32_e32 v3, v21, v6
	v_mul_f32_e32 v9, v82, v6
	v_mul_f32_e32 v12, v83, v6
	v_cvt_pk_fp8_f32 v64, v16, v17
	v_mul_f32_e32 v8, v23, v6
	v_mul_f32_e32 v17, v94, v6
	v_mul_f32_e32 v20, v95, v6
	v_mul_f32_e32 v23, v86, v6
	v_mul_f32_e32 v24, v87, v6
	v_cvt_pk_fp8_f32 v106, v2, v3
	v_cvt_pk_fp8_f32 v107, v9, v12
	v_cvt_pk_fp8_f32 v108, v17, v20
	v_cvt_pk_fp8_f32 v109, v23, v24
	v_mul_f32_e32 v10, v18, v7
	v_mul_f32_e32 v11, v19, v7
	v_mul_f32_e32 v14, v7, v26
	v_mul_f32_e32 v15, v7, v27
	v_mul_f32_e32 v18, v7, v92
	v_mul_f32_e32 v19, v7, v93
	v_mul_f32_e32 v4, v7, v4
	v_mul_f32_e32 v5, v7, v5
	v_mul_f32_e32 v7, v22, v6
	v_mul_f32_e32 v13, v84, v6
	v_mul_f32_e32 v16, v85, v6
	v_mul_f32_e32 v21, v96, v6
	v_mul_f32_e32 v22, v97, v6
	v_mul_f32_e32 v25, v88, v6
	v_mul_f32_e32 v6, v89, v6
	v_cvt_pk_fp8_f32 v28, v10, v11 op_sel:[0,0,1]
	v_cvt_pk_fp8_f32 v29, v14, v15 op_sel:[0,0,1]
	v_cvt_pk_fp8_f32 v106, v7, v8 op_sel:[0,0,1]
	v_cvt_pk_fp8_f32 v107, v13, v16 op_sel:[0,0,1]
	v_cvt_pk_fp8_f32 v64, v18, v19 op_sel:[0,0,1]
	v_cvt_pk_fp8_f32 v65, v4, v5 op_sel:[0,0,1]
	v_cvt_pk_fp8_f32 v108, v21, v22 op_sel:[0,0,1]
	v_cvt_pk_fp8_f32 v109, v25, v6 op_sel:[0,0,1]
	v_permlane16_swap_b32_e32 v28, v29
	v_permlane16_swap_b32_e32 v106, v107
	s_mov_b64 vcc, s[0:1]
	v_permlane16_swap_b32_e32 v64, v65
	global_store_dwordx2 v[98:99], v[28:29], off sc1
	global_store_dwordx2 v[98:99], v[64:65], off offset:32 sc1
	v_permlane16_swap_b32_e32 v108, v109
	global_store_dwordx2 v[100:101], v[106:107], off sc1
	global_store_dwordx2 v[100:101], v[108:109], off offset:32 sc1
	s_barrier
	s_cbranch_vccnz .LBB0_921
	s_add_i32 s40, s40, s88
	s_cmpk_lt_i32 s40, 0x100
	s_cbranch_scc1 .LBB0_920

; #define LAS __attribute__((address_space(3)))
; template <bool ENGINE, int ESTEPS>
; __device__ __forceinline__ void moba_sparse(const Frame& F, const Args& a, int rep) {
;     ...
;         unsigned* qctr = (unsigned*)(F.ctl + CW_QUEUE + 64 * (xg * 3 + bl) + 2048 * rep);
;         __syncthreads();
;         for (int i = tid; i < NBLK * OFFS_LD / 2; i += 512) ((LAS unsigned*)offs)[i] = ((const unsigned*)(OFFS + (size_t)bh * NBLK * OFFS_LD))[i];
;         if (tid == 0) { itq[0] = (int)__hip_atomic_fetch_add(qctr, 1u, RLX_AGENT); itq[1] = (int)__hip_atomic_fetch_add(qctr, 1u, RLX_AGENT); }
.LBB0_977:
	s_mov_b64 s[4:5], 0x1000
	v_lshl_add_u64 v[242:243], v[18:19], 0, s[4:5]
	s_mov_b64 s[4:5], 0x2000
	v_lshl_add_u64 v[244:245], v[18:19], 0, s[4:5]
	global_load_dword v22, v[18:19], off
	global_load_dword v240, v[18:19], off offset:2048
	global_load_dword v241, v[242:243], off
	global_load_dword v246, v[242:243], off offset:2048
	v_cmp_gt_u32_e32 vcc, 0x80, v0
	s_and_saveexec_b64 s[0:1], vcc
	global_load_dword v247, v[244:245], off
	s_or_b64 exec, exec, s[0:1]
	s_waitcnt vmcnt(0)
	ds_write_b32 v20, v22
	ds_write_b32 v20, v240 offset:2048
	ds_write_b32 v20, v241 offset:4096
	ds_write_b32 v20, v246 offset:6144
	s_and_saveexec_b64 s[0:1], vcc
	ds_write_b32 v20, v247 offset:8192
	s_or_b64 exec, exec, s[0:1]
	s_mul_i32 s0, s57, 3
	s_add_i32 s0, s86, s0
	s_lshl_b32 s0, s0, 6
	s_ashr_i32 s1, s0, 31
	s_lshl_b64 s[0:1], s[0:1], 2
	s_add_u32 s92, s14, s0
	s_addc_u32 s93, s15, s1
	s_and_saveexec_b64 s[0:1], s[2:3]
	s_cbranch_execz .LBB0_984
	s_mov_b64 s[6:7], exec
	v_mbcnt_lo_u32_b32 v18, s6, 0
	v_mbcnt_hi_u32_b32 v18, s7, v18
	v_cmp_eq_u32_e32 vcc, 0, v18
	s_and_saveexec_b64 s[4:5], vcc
	s_cbranch_execz .LBB0_981
	s_bcnt1_i32_b64 s6, s[6:7]
	v_mov_b32_e32 v19, s6
	global_atomic_add v19, v47, v19, s[92:93] sc0
